# grid barrier: non-leader workgroups poll the cross-XCD release word directly; XCD leader no longer does the per-XCD release atomic and its ack wait
# speedup vs baseline: 1.0171x; 1.0041x over previous
; __device__ __forceinline__ unsigned xb_ld(unsigned* p)              { return __hip_atomic_load(p, __ATOMIC_RELAXED, __HIP_MEMORY_SCOPE_AGENT); }
; __device__ __forceinline__ unsigned xb_add(unsigned* p, unsigned v) { return __hip_atomic_fetch_add(p, v, __ATOMIC_RELAXED, __HIP_MEMORY_SCOPE_AGENT); }
; #define XB_SPIN(cond, bar) do { unsigned _sp = 0; while (cond) { __builtin_amdgcn_s_sleep(1); \
;     if ((++_sp & 255u) == 0u) { if (xb_ld(&(bar)[XB_TMO])) break; if (_sp > XB_SPIN_CAP) { atomicAdd(&(bar)[XB_TMO], 1u); break; } } } } while (0)
; __device__ __forceinline__ void xcd_barrier(const XcdBarrier& b) {
;     ...
;             if (og + 1u == (tg + 1u) * nx) xb_add(&bar[XB_TOPGEN], 1u);
;             else XB_SPIN(xb_ld(&bar[XB_TOPGEN]) == tg, bar);
;             __builtin_amdgcn_fence(__ATOMIC_ACQUIRE, "agent");
;             xb_add(&bar[XB_XGEN(b.x)], 1u);
;             asm volatile("s_waitcnt vmcnt(0)" ::: "memory");
.LBB0_223:
	s_or_b64 exec, exec, s[2:3]
	s_waitcnt vmcnt(0)
	buffer_inv sc1
	s_waitcnt vmcnt(0)

; __device__ __forceinline__ unsigned xb_ld(unsigned* p)              { return __hip_atomic_load(p, __ATOMIC_RELAXED, __HIP_MEMORY_SCOPE_AGENT); }
; __device__ __forceinline__ unsigned xb_add(unsigned* p, unsigned v) { return __hip_atomic_fetch_add(p, v, __ATOMIC_RELAXED, __HIP_MEMORY_SCOPE_AGENT); }
; #define XB_SPIN(cond, bar) do { unsigned _sp = 0; while (cond) { __builtin_amdgcn_s_sleep(1); \
;     if ((++_sp & 255u) == 0u) { if (xb_ld(&(bar)[XB_TMO])) break; if (_sp > XB_SPIN_CAP) { atomicAdd(&(bar)[XB_TMO], 1u); break; } } } } while (0)
; __device__ __forceinline__ void xcd_barrier(const XcdBarrier& b) {
;     ...
;         const unsigned old = xb_add(&bar[XB_XSUB(b.x)], 1u);
;         const unsigned gen = old / nloc;
;         if (old + 1u == (gen + 1u) * nloc) {
;             __builtin_amdgcn_fence(__ATOMIC_RELEASE, "agent");
;             asm volatile("s_waitcnt vmcnt(0)" ::: "memory");
;             const unsigned og = xb_add(&bar[XB_TOP], 1u);
;             const unsigned tg = og / nx;
;             if (og + 1u == (tg + 1u) * nx) xb_add(&bar[XB_TOPGEN], 1u);
;             else XB_SPIN(xb_ld(&bar[XB_TOPGEN]) == tg, bar);
;             __builtin_amdgcn_fence(__ATOMIC_ACQUIRE, "agent");
;             xb_add(&bar[XB_XGEN(b.x)], 1u);
;             asm volatile("s_waitcnt vmcnt(0)" ::: "memory");
;         } else {
;             XB_SPIN(xb_ld(&bar[XB_XGEN(b.x)]) == gen, bar);
;             __builtin_amdgcn_fence(__ATOMIC_ACQUIRE, "agent");
;             asm volatile("s_waitcnt vmcnt(0)" ::: "memory");
.LBB0_1828:
	global_atomic_add v3, v[192:193], v206, off sc0
	v_cvt_f32_u32_e32 v1, v2
	v_sub_u32_e32 v4, 0, v2
	v_rcp_iflag_f32_e32 v1, v1
	s_nop 0
	v_mul_f32_e32 v1, 0x4f7ffffe, v1
	v_cvt_u32_f32_e32 v1, v1
	v_mul_lo_u32 v4, v4, v1
	v_mul_hi_u32 v4, v1, v4
	v_add_u32_e32 v1, v1, v4
	s_waitcnt vmcnt(0)
	v_mul_hi_u32 v1, v3, v1
	v_mul_lo_u32 v4, v1, v2
	v_sub_u32_e32 v4, v3, v4
	v_add_u32_e32 v5, 1, v1
	v_cmp_ge_u32_e32 vcc, v4, v2
	v_add_u32_e32 v3, 1, v3
	s_nop 0
	v_cndmask_b32_e32 v1, v1, v5, vcc
	v_sub_u32_e32 v5, v4, v2
	v_cndmask_b32_e32 v4, v4, v5, vcc
	v_add_u32_e32 v5, 1, v1
	v_cmp_ge_u32_e32 vcc, v4, v2
	s_nop 1
	v_cndmask_b32_e32 v1, v1, v5, vcc
	v_mul_lo_u32 v4, v2, v1
	v_add_u32_e32 v2, v4, v2
	v_cmp_ne_u32_e32 vcc, v3, v2
	s_and_saveexec_b64 s[2:3], vcc
	s_xor_b64 s[2:3], exec, s[2:3]
	s_cbranch_execz .LBB0_1842
	s_waitcnt lgkmcnt(0)
	v_readlane_b32 s4, v251, 29
	v_readlane_b32 s5, v251, 30
	s_nop 4
	global_load_dword v0, v197, s[4:5] sc1
	s_waitcnt vmcnt(0)
	v_cmp_eq_u32_e32 vcc, v0, v1
	s_and_saveexec_b64 s[18:19], vcc
	s_cbranch_execz .LBB0_1841
	s_mov_b32 s21, 1
	s_mov_b64 s[24:25], 0
	s_branch .LBB0_1832

; __device__ __forceinline__ unsigned xb_ld(unsigned* p)              { return __hip_atomic_load(p, __ATOMIC_RELAXED, __HIP_MEMORY_SCOPE_AGENT); }
; #define XB_SPIN(cond, bar) do { unsigned _sp = 0; while (cond) { __builtin_amdgcn_s_sleep(1); \
;     if ((++_sp & 255u) == 0u) { if (xb_ld(&(bar)[XB_TMO])) break; if (_sp > XB_SPIN_CAP) { atomicAdd(&(bar)[XB_TMO], 1u); break; } } } } while (0)
; __device__ __forceinline__ void xcd_barrier(const XcdBarrier& b) {
;     ...
;             XB_SPIN(xb_ld(&bar[XB_XGEN(b.x)]) == gen, bar);
.LBB0_1836:
	v_readlane_b32 s4, v251, 29
	v_readlane_b32 s5, v251, 30
	s_nop 4
	global_load_dword v0, v197, s[4:5] sc1
	s_add_i32 s21, s21, 1
	s_mov_b64 s[38:39], -1
	s_waitcnt vmcnt(0)
	v_cmp_ne_u32_e32 vcc, v0, v1
	s_orn2_b64 s[34:35], vcc, exec
	s_branch .LBB0_1831
